# q0 round-4 idle workgroups (204..255) convert the last 2288 tiles of layer 0's weight list; q3 converts the remaining 2352
# speedup vs baseline: 1.0068x; 1.0068x over previous
.LBB0_139:
	s_barrier
	v_readlane_b32 s4, v239, 37
	v_readlane_b32 s5, v241, 0
	v_readlane_b32 s6, v241, 9
	s_cmp_lg_u32 s4, 0
	s_cbranch_scc1 .LBB0_140
	s_cmpk_lt_i32 s5, 0xcc
	s_cbranch_scc1 .LBB0_140
	s_cmpk_lg_i32 s6, 0x100
	s_cbranch_scc1 .LBB0_140
	s_add_i32 s56, s5, 0xffffff34
	s_mov_b32 s8, 0
	v_readlane_b32 s14, v239, 42
	v_readlane_b32 s15, v239, 43
	v_lshrrev_b32_e32 v117, 5, v178
	v_and_b32_e32 v168, 31, v178
	v_lshlrev_b32_e32 v116, 2, v168
	v_mul_u32_u24_e32 v16, 0x204, v117
	v_lshl_add_u32 v16, v116, 2, v16
	v_and_b32_e32 v168, 7, v178
	v_lshlrev_b32_e32 v120, 4, v168
	v_mul_u32_u24_e32 v17, 0x1020, v168
	v_lshrrev_b32_e32 v119, 3, v178
	v_lshl_add_u32 v17, v119, 2, v17
	s_add_i32 s4, s56, 4080
	s_mov_b32 s39, 0
	s_cmpk_lt_u32 s4, 0x6c0
	s_cbranch_scc0 .Ltrq0_t1_0
	s_lshr_b32 s5, s4, 5
	s_and_b32 s6, s4, 31
	v_readlane_b32 s28, v241, 11
	v_readlane_b32 s29, v241, 12
	s_mul_i32 s9, s8, 0x3430000
	s_movk_i32 s38, 0x6860
	s_mov_b32 s2, 0
	s_mul_i32 s3, s8, 0x1b00000
	s_movk_i32 s44, 0x1000
	s_mov_b32 s39, 1
	s_branch .Ltrq0_dec_0

.Ltrq0_nosc:
	v_mov_b32_e32 v168, v16
	ds_write2_b32 v168, v100, v101 offset1:1
	ds_write2_b32 v168, v102, v103 offset0:2 offset1:3
	v_add_u32_e32 v168, 8256, v16
	ds_write2_b32 v168, v104, v105 offset1:1
	ds_write2_b32 v168, v106, v107 offset0:2 offset1:3
	v_add_u32_e32 v168, 16512, v16
	ds_write2_b32 v168, v108, v109 offset1:1
	ds_write2_b32 v168, v110, v111 offset0:2 offset1:3
	v_add_u32_e32 v168, 24768, v16
	ds_write2_b32 v168, v112, v113 offset1:1
	ds_write2_b32 v168, v114, v115 offset0:2 offset1:3
	s_add_i32 s56, s56, 52
	s_cmpk_lt_u32 s56, 0x8f0
	s_cselect_b32 s7, 1, 0
	s_cbranch_scc0 .Ltrq0_nonext
	s_add_i32 s4, s56, 4080
	s_mov_b32 s39, 0
	s_cmpk_lt_u32 s4, 0x6c0
	s_cbranch_scc0 .Ltrq0_t1_1
	s_lshr_b32 s5, s4, 5
	s_and_b32 s6, s4, 31
	v_readlane_b32 s28, v241, 11
	v_readlane_b32 s29, v241, 12
	s_mul_i32 s9, s8, 0x3430000
	s_movk_i32 s38, 0x6860
	s_mov_b32 s2, 0
	s_mul_i32 s3, s8, 0x1b00000
	s_movk_i32 s44, 0x1000
	s_mov_b32 s39, 1
	s_branch .Ltrq0_dec_1

.Ltrq3a_nosc:
	v_mov_b32_e32 v168, v16
	ds_write2_b32 v168, v100, v101 offset1:1
	ds_write2_b32 v168, v102, v103 offset0:2 offset1:3
	v_add_u32_e32 v168, 8256, v16
	ds_write2_b32 v168, v104, v105 offset1:1
	ds_write2_b32 v168, v106, v107 offset0:2 offset1:3
	v_add_u32_e32 v168, 16512, v16
	ds_write2_b32 v168, v108, v109 offset1:1
	ds_write2_b32 v168, v110, v111 offset0:2 offset1:3
	v_add_u32_e32 v168, 24768, v16
	ds_write2_b32 v168, v112, v113 offset1:1
	ds_write2_b32 v168, v114, v115 offset0:2 offset1:3
	s_add_i32 s70, s70, 256
	s_cmpk_lt_u32 s70, 0x930
	s_cselect_b32 s7, 1, 0
	s_cbranch_scc0 .Ltrq3a_nonext
	s_add_i32 s4, s70, 1728
	s_mov_b32 s39, 0
	s_cmpk_lt_u32 s4, 0x6c0
	s_cbranch_scc0 .Ltrq3a_t1_1
	s_lshr_b32 s5, s4, 5
	s_and_b32 s6, s4, 31
	v_readlane_b32 s28, v241, 11
	v_readlane_b32 s29, v241, 12
	s_mul_i32 s9, s8, 0x3430000
	s_movk_i32 s38, 0x6860
	s_mov_b32 s2, 0
	s_mul_i32 s3, s8, 0x1b00000
	s_movk_i32 s44, 0x1000
	s_mov_b32 s39, 1
	s_branch .Ltrq3a_dec_1

.Ltrq3b_nosc:
	v_mov_b32_e32 v168, v16
	ds_write2_b32 v168, v100, v101 offset1:1
	ds_write2_b32 v168, v102, v103 offset0:2 offset1:3
	v_add_u32_e32 v168, 8256, v16
	ds_write2_b32 v168, v104, v105 offset1:1
	ds_write2_b32 v168, v106, v107 offset0:2 offset1:3
	v_add_u32_e32 v168, 16512, v16
	ds_write2_b32 v168, v108, v109 offset1:1
	ds_write2_b32 v168, v110, v111 offset0:2 offset1:3
	v_add_u32_e32 v168, 24768, v16
	ds_write2_b32 v168, v112, v113 offset1:1
	ds_write2_b32 v168, v114, v115 offset0:2 offset1:3
	s_add_i32 s68, s68, 256
	s_cmpk_lt_u32 s68, 0x930
	s_cselect_b32 s7, 1, 0
	s_cbranch_scc0 .Ltrq3b_nonext
	s_add_i32 s4, s68, 1728
	s_mov_b32 s39, 0
	s_cmpk_lt_u32 s4, 0x6c0
	s_cbranch_scc0 .Ltrq3b_t1_1
	s_lshr_b32 s5, s4, 5
	s_and_b32 s6, s4, 31
	v_readlane_b32 s28, v241, 11
	v_readlane_b32 s29, v241, 12
	s_mul_i32 s9, s8, 0x3430000
	s_movk_i32 s38, 0x6860
	s_mov_b32 s2, 0
	s_mul_i32 s3, s8, 0x1b00000
	s_movk_i32 s44, 0x1000
	s_mov_b32 s39, 1
	s_branch .Ltrq3b_dec_1
